# narrow LoRA tiles (M_VLW, pn>=4) use a K-loop variant without the unused column-half MFMAs (on top of the 4-phase K-loop)
# speedup vs baseline: 1.0108x; 1.0108x over previous
.LBB0_918:
	s_add_u32 s38, s18, 0x100
	s_addc_u32 s39, s19, 0
	s_add_u32 s18, s20, 0x80
	v_mov_b32_e32 v2, 0
	s_addc_u32 s19, s21, 0
	s_mov_b32 s20, 0
	v_mov_b32_e32 v3, v2
	v_mov_b32_e32 v4, v2
	v_mov_b32_e32 v5, v2
	v_mov_b32_e32 v6, v2
	v_mov_b32_e32 v7, v2
	v_mov_b32_e32 v8, v2
	v_mov_b32_e32 v9, v2
	v_mov_b32_e32 v18, v2
	v_mov_b32_e32 v19, v2
	v_mov_b32_e32 v20, v2
	v_mov_b32_e32 v21, v2
	v_mov_b32_e32 v22, v2
	v_mov_b32_e32 v23, v2
	v_mov_b32_e32 v24, v2
	v_mov_b32_e32 v25, v2
	v_mov_b32_e32 v34, v2
	v_mov_b32_e32 v35, v2
	v_mov_b32_e32 v36, v2
	v_mov_b32_e32 v37, v2
	v_mov_b32_e32 v38, v2
	v_mov_b32_e32 v39, v2
	v_mov_b32_e32 v40, v2
	v_mov_b32_e32 v41, v2
	v_mov_b32_e32 v50, v2
	v_mov_b32_e32 v51, v2
	v_mov_b32_e32 v52, v2
	v_mov_b32_e32 v53, v2
	v_mov_b32_e32 v54, v2
	v_mov_b32_e32 v55, v2
	v_mov_b32_e32 v56, v2
	v_mov_b32_e32 v57, v2
	v_mov_b32_e32 v10, v2
	v_mov_b32_e32 v11, v2
	v_mov_b32_e32 v12, v2
	v_mov_b32_e32 v13, v2
	v_mov_b32_e32 v14, v2
	v_mov_b32_e32 v15, v2
	v_mov_b32_e32 v16, v2
	v_mov_b32_e32 v17, v2
	v_mov_b32_e32 v26, v2
	v_mov_b32_e32 v27, v2
	v_mov_b32_e32 v28, v2
	v_mov_b32_e32 v29, v2
	v_mov_b32_e32 v30, v2
	v_mov_b32_e32 v31, v2
	v_mov_b32_e32 v32, v2
	v_mov_b32_e32 v33, v2
	v_mov_b32_e32 v42, v2
	v_mov_b32_e32 v43, v2
	v_mov_b32_e32 v44, v2
	v_mov_b32_e32 v45, v2
	v_mov_b32_e32 v46, v2
	v_mov_b32_e32 v47, v2
	v_mov_b32_e32 v48, v2
	v_mov_b32_e32 v49, v2
	v_mov_b32_e32 v58, v2
	v_mov_b32_e32 v59, v2
	v_mov_b32_e32 v60, v2
	v_mov_b32_e32 v61, v2
	v_mov_b32_e32 v62, v2
	v_mov_b32_e32 v63, v2
	v_mov_b32_e32 v64, v2
	v_mov_b32_e32 v65, v2
	v_mov_b32_e32 v66, v2
	v_mov_b32_e32 v67, v2
	v_mov_b32_e32 v68, v2
	v_mov_b32_e32 v69, v2
	v_mov_b32_e32 v70, v2
	v_mov_b32_e32 v71, v2
	v_mov_b32_e32 v72, v2
	v_mov_b32_e32 v73, v2
	v_mov_b32_e32 v82, v2
	v_mov_b32_e32 v83, v2
	v_mov_b32_e32 v84, v2
	v_mov_b32_e32 v85, v2
	v_mov_b32_e32 v86, v2
	v_mov_b32_e32 v87, v2
	v_mov_b32_e32 v88, v2
	v_mov_b32_e32 v89, v2
	v_mov_b32_e32 v98, v2
	v_mov_b32_e32 v99, v2
	v_mov_b32_e32 v100, v2
	v_mov_b32_e32 v101, v2
	v_mov_b32_e32 v102, v2
	v_mov_b32_e32 v103, v2
	v_mov_b32_e32 v104, v2
	v_mov_b32_e32 v105, v2
	v_mov_b32_e32 v114, v2
	v_mov_b32_e32 v115, v2
	v_mov_b32_e32 v116, v2
	v_mov_b32_e32 v117, v2
	v_mov_b32_e32 v118, v2
	v_mov_b32_e32 v119, v2
	v_mov_b32_e32 v120, v2
	v_mov_b32_e32 v121, v2
	v_mov_b32_e32 v74, v2
	v_mov_b32_e32 v75, v2
	v_mov_b32_e32 v76, v2
	v_mov_b32_e32 v77, v2
	v_mov_b32_e32 v78, v2
	v_mov_b32_e32 v79, v2
	v_mov_b32_e32 v80, v2
	v_mov_b32_e32 v81, v2
	v_mov_b32_e32 v90, v2
	v_mov_b32_e32 v91, v2
	v_mov_b32_e32 v92, v2
	v_mov_b32_e32 v93, v2
	v_mov_b32_e32 v94, v2
	v_mov_b32_e32 v95, v2
	v_mov_b32_e32 v96, v2
	v_mov_b32_e32 v97, v2
	v_mov_b32_e32 v106, v2
	v_mov_b32_e32 v107, v2
	v_mov_b32_e32 v108, v2
	v_mov_b32_e32 v109, v2
	v_mov_b32_e32 v110, v2
	v_mov_b32_e32 v111, v2
	v_mov_b32_e32 v112, v2
	v_mov_b32_e32 v113, v2
	v_mov_b32_e32 v122, v2
	v_mov_b32_e32 v123, v2
	v_mov_b32_e32 v124, v2
	v_mov_b32_e32 v125, v2
	v_mov_b32_e32 v126, v2
	v_mov_b32_e32 v127, v2
	v_mov_b32_e32 v128, v2
	v_mov_b32_e32 v129, v2
	s_cmp_eq_u32 s96, 1
	s_cselect_b32 s100, s5, 0
	s_cmp_gt_i32 s100, 3
	s_cbranch_scc1 .Lkloop_narrow
.LBB0_919:
	s_add_i32 s42, s20, 2
	s_add_u32 s24, s18, 0x80
	s_addc_u32 s21, s19, 0
	s_add_i32 s43, 0, 0x10000
	v_add_u32_e32 v0, s43, v211
	s_waitcnt lgkmcnt(0)
	ds_read_b128 v[130:133], v0
	ds_read_b128 v[134:137], v0 offset:1024
	ds_read_b128 v[138:141], v0 offset:2048
	ds_read_b128 v[142:145], v0 offset:3072
	s_cmp_eq_u32 s66, s20
	s_cselect_b32 s20, s74, s24
	s_cselect_b32 s21, s75, s21
	s_cselect_b32 s25, s77, s39
	s_cselect_b32 s24, s76, s38
	s_add_i32 s44, 0, 0x14000
	v_add_u32_e32 v0, s44, v211
	v_lshl_add_u64 v[198:199], s[18:19], 0, v[184:185]
	s_add_i32 m0, s31, 0xc000
	ds_read_b128 v[232:235], v0
	ds_read_b128 v[236:239], v0 offset:1024
	ds_read_b128 v[240:243], v0 offset:2048
	ds_read_b128 v[244:247], v0 offset:3072
	global_load_lds_dwordx4 v[198:199], off
	v_lshl_add_u64 v[198:199], s[18:19], 0, v[182:183]
	s_add_i32 m0, s31, 0xe000
	s_nop 0
	global_load_lds_dwordx4 v[198:199], off
	ds_read_b128 v[146:149], v212
	ds_read_b128 v[150:153], v212 offset:1024
	ds_read_b128 v[154:157], v212 offset:2048
	ds_read_b128 v[158:161], v212 offset:3072
	ds_read_b128 v[186:189], v212 offset:4096
	ds_read_b128 v[190:193], v212 offset:5120
	s_waitcnt lgkmcnt(12)
	ds_read_b128 v[194:197], v212 offset:6144
	ds_read_b128 v[214:217], v212 offset:7168
	s_waitcnt vmcnt(8) lgkmcnt(0)
	s_barrier
	s_setprio 1
	v_mfma_f32_16x16x32_bf16 v[126:129], v[130:133], v[146:149], v[126:129]
	v_mfma_f32_16x16x32_bf16 v[122:125], v[138:141], v[146:149], v[122:125]
	v_mfma_f32_16x16x32_bf16 v[110:113], v[130:133], v[154:157], v[110:113]
	v_mfma_f32_16x16x32_bf16 v[106:109], v[138:141], v[154:157], v[106:109]
	v_mfma_f32_16x16x32_bf16 v[94:97], v[130:133], v[186:189], v[94:97]
	v_mfma_f32_16x16x32_bf16 v[90:93], v[138:141], v[186:189], v[90:93]
	v_mfma_f32_16x16x32_bf16 v[78:81], v[130:133], v[194:197], v[78:81]
	v_mfma_f32_16x16x32_bf16 v[74:77], v[138:141], v[194:197], v[74:77]
	v_mfma_f32_16x16x32_bf16 v[126:129], v[134:137], v[150:153], v[126:129]
	v_mfma_f32_16x16x32_bf16 v[122:125], v[142:145], v[150:153], v[122:125]
	v_mfma_f32_16x16x32_bf16 v[110:113], v[134:137], v[158:161], v[110:113]
	v_mfma_f32_16x16x32_bf16 v[106:109], v[142:145], v[158:161], v[106:109]
	v_mfma_f32_16x16x32_bf16 v[94:97], v[134:137], v[190:193], v[94:97]
	v_mfma_f32_16x16x32_bf16 v[90:93], v[142:145], v[190:193], v[90:93]
	v_mfma_f32_16x16x32_bf16 v[78:81], v[134:137], v[214:217], v[78:81]
	v_mfma_f32_16x16x32_bf16 v[74:77], v[142:145], v[214:217], v[74:77]
	v_mfma_f32_16x16x32_bf16 v[118:121], v[232:235], v[146:149], v[118:121]
	v_mfma_f32_16x16x32_bf16 v[114:117], v[240:243], v[146:149], v[114:117]
	v_mfma_f32_16x16x32_bf16 v[102:105], v[232:235], v[154:157], v[102:105]
	v_mfma_f32_16x16x32_bf16 v[98:101], v[240:243], v[154:157], v[98:101]
	v_mfma_f32_16x16x32_bf16 v[86:89], v[232:235], v[186:189], v[86:89]
	v_mfma_f32_16x16x32_bf16 v[82:85], v[240:243], v[186:189], v[82:85]
	v_mfma_f32_16x16x32_bf16 v[70:73], v[232:235], v[194:197], v[70:73]
	v_mfma_f32_16x16x32_bf16 v[66:69], v[240:243], v[194:197], v[66:69]
	v_mfma_f32_16x16x32_bf16 v[118:121], v[236:239], v[150:153], v[118:121]
	v_mfma_f32_16x16x32_bf16 v[114:117], v[244:247], v[150:153], v[114:117]
	v_mfma_f32_16x16x32_bf16 v[102:105], v[236:239], v[158:161], v[102:105]
	v_mfma_f32_16x16x32_bf16 v[98:101], v[244:247], v[158:161], v[98:101]
	v_mfma_f32_16x16x32_bf16 v[86:89], v[236:239], v[190:193], v[86:89]
	v_mfma_f32_16x16x32_bf16 v[82:85], v[244:247], v[190:193], v[82:85]
	v_mfma_f32_16x16x32_bf16 v[70:73], v[236:239], v[214:217], v[70:73]
	v_mfma_f32_16x16x32_bf16 v[66:69], v[244:247], v[214:217], v[66:69]
	s_setprio 0
	s_barrier
	ds_read_b128 v[146:149], v212 offset:16384
	ds_read_b128 v[150:153], v212 offset:17408
	ds_read_b128 v[154:157], v212 offset:18432
	ds_read_b128 v[158:161], v212 offset:19456
	ds_read_b128 v[186:189], v212 offset:20480
	ds_read_b128 v[190:193], v212 offset:21504
	ds_read_b128 v[194:197], v212 offset:22528
	ds_read_b128 v[214:217], v212 offset:23552
	s_add_i32 s43, s43, s30
	v_lshl_add_u64 v[198:199], s[24:25], 0, v[170:171]
	s_mov_b32 m0, s43
	v_lshl_add_u64 v[218:219], s[24:25], 0, v[174:175]
	global_load_lds_dwordx4 v[198:199], off
	s_add_i32 m0, s43, 0x2000
	s_nop 0
	global_load_lds_dwordx4 v[218:219], off
	s_mov_b32 m0, s31
	v_lshl_add_u64 v[248:249], s[20:21], 0, v[168:169]
	v_lshl_add_u64 v[250:251], s[20:21], 0, v[172:173]
	global_load_lds_dwordx4 v[248:249], off
	s_mov_b32 m0, s95
	s_nop 0
	global_load_lds_dwordx4 v[250:251], off
	s_add_u32 s24, s24, s60
	s_addc_u32 s25, s25, 0
	s_add_i32 s43, s44, s30
	v_lshl_add_u64 v[226:227], s[24:25], 0, v[170:171]
	s_mov_b32 m0, s43
	v_lshl_add_u64 v[228:229], s[24:25], 0, v[174:175]
	global_load_lds_dwordx4 v[226:227], off
	s_add_i32 m0, s43, 0x2000
	s_nop 0
	global_load_lds_dwordx4 v[228:229], off
	s_waitcnt vmcnt(8) lgkmcnt(0)
	s_barrier
	s_setprio 1
	v_mfma_f32_16x16x32_bf16 v[62:65], v[130:133], v[146:149], v[62:65]
	v_mfma_f32_16x16x32_bf16 v[58:61], v[138:141], v[146:149], v[58:61]
	v_mfma_f32_16x16x32_bf16 v[46:49], v[130:133], v[154:157], v[46:49]
	v_mfma_f32_16x16x32_bf16 v[42:45], v[138:141], v[154:157], v[42:45]
	v_mfma_f32_16x16x32_bf16 v[30:33], v[130:133], v[186:189], v[30:33]
	v_mfma_f32_16x16x32_bf16 v[26:29], v[138:141], v[186:189], v[26:29]
	v_mfma_f32_16x16x32_bf16 v[14:17], v[130:133], v[194:197], v[14:17]
	v_mfma_f32_16x16x32_bf16 v[10:13], v[138:141], v[194:197], v[10:13]
	v_mfma_f32_16x16x32_bf16 v[62:65], v[134:137], v[150:153], v[62:65]
	v_mfma_f32_16x16x32_bf16 v[58:61], v[142:145], v[150:153], v[58:61]
	v_mfma_f32_16x16x32_bf16 v[46:49], v[134:137], v[158:161], v[46:49]
	v_mfma_f32_16x16x32_bf16 v[42:45], v[142:145], v[158:161], v[42:45]
	v_mfma_f32_16x16x32_bf16 v[30:33], v[134:137], v[190:193], v[30:33]
	v_mfma_f32_16x16x32_bf16 v[26:29], v[142:145], v[190:193], v[26:29]
	v_mfma_f32_16x16x32_bf16 v[14:17], v[134:137], v[214:217], v[14:17]
	v_mfma_f32_16x16x32_bf16 v[10:13], v[142:145], v[214:217], v[10:13]
	v_mfma_f32_16x16x32_bf16 v[54:57], v[232:235], v[146:149], v[54:57]
	v_mfma_f32_16x16x32_bf16 v[50:53], v[240:243], v[146:149], v[50:53]
	v_mfma_f32_16x16x32_bf16 v[38:41], v[232:235], v[154:157], v[38:41]
	v_mfma_f32_16x16x32_bf16 v[34:37], v[240:243], v[154:157], v[34:37]
	v_mfma_f32_16x16x32_bf16 v[22:25], v[232:235], v[186:189], v[22:25]
	v_mfma_f32_16x16x32_bf16 v[18:21], v[240:243], v[186:189], v[18:21]
	v_mfma_f32_16x16x32_bf16 v[6:9], v[232:235], v[194:197], v[6:9]
	v_mfma_f32_16x16x32_bf16 v[2:5], v[240:243], v[194:197], v[2:5]
	v_mfma_f32_16x16x32_bf16 v[54:57], v[236:239], v[150:153], v[54:57]
	v_mfma_f32_16x16x32_bf16 v[50:53], v[244:247], v[150:153], v[50:53]
	v_mfma_f32_16x16x32_bf16 v[38:41], v[236:239], v[158:161], v[38:41]
	v_mfma_f32_16x16x32_bf16 v[34:37], v[244:247], v[158:161], v[34:37]
	v_mfma_f32_16x16x32_bf16 v[22:25], v[236:239], v[190:193], v[22:25]
	v_mfma_f32_16x16x32_bf16 v[18:21], v[244:247], v[190:193], v[18:21]
	v_mfma_f32_16x16x32_bf16 v[6:9], v[236:239], v[214:217], v[6:9]
	v_mfma_f32_16x16x32_bf16 v[2:5], v[244:247], v[214:217], v[2:5]
	s_setprio 0
	s_barrier
	s_add_u32 s20, s20, s60
	s_addc_u32 s21, s21, 0
	s_mov_b32 m0, s8
	v_lshl_add_u64 v[232:233], s[20:21], 0, v[168:169]
	s_add_i32 s24, 0, 0x18000
	v_add_u32_e32 v0, s24, v211
	global_load_lds_dwordx4 v[232:233], off
	v_lshl_add_u64 v[232:233], s[20:21], 0, v[172:173]
	s_mov_b32 m0, s9
	s_nop 0
	global_load_lds_dwordx4 v[232:233], off
	ds_read_b128 v[130:133], v0
	ds_read_b128 v[134:137], v0 offset:1024
	ds_read_b128 v[138:141], v0 offset:2048
	ds_read_b128 v[142:145], v0 offset:3072
	s_add_i32 s20, 0, 0x1c000
	s_add_i32 s21, s24, s30
	v_add_u32_e32 v0, s20, v211
	ds_read_b128 v[232:235], v0
	ds_read_b128 v[236:239], v0 offset:1024
	ds_read_b128 v[240:243], v0 offset:2048
	ds_read_b128 v[244:247], v0 offset:3072
	ds_read_b128 v[146:149], v212 offset:32768
	ds_read_b128 v[150:153], v212 offset:33792
	ds_read_b128 v[154:157], v212 offset:34816
	ds_read_b128 v[158:161], v212 offset:35840
	ds_read_b128 v[186:189], v212 offset:36864
	ds_read_b128 v[190:193], v212 offset:37888
	s_waitcnt lgkmcnt(12)
	ds_read_b128 v[194:197], v212 offset:38912
	ds_read_b128 v[214:217], v212 offset:39936
	s_waitcnt vmcnt(8) lgkmcnt(0)
	s_barrier
	s_setprio 1
	v_mfma_f32_16x16x32_bf16 v[126:129], v[130:133], v[146:149], v[126:129]
	v_mfma_f32_16x16x32_bf16 v[122:125], v[138:141], v[146:149], v[122:125]
	v_mfma_f32_16x16x32_bf16 v[110:113], v[130:133], v[154:157], v[110:113]
	v_mfma_f32_16x16x32_bf16 v[106:109], v[138:141], v[154:157], v[106:109]
	v_mfma_f32_16x16x32_bf16 v[94:97], v[130:133], v[186:189], v[94:97]
	v_mfma_f32_16x16x32_bf16 v[90:93], v[138:141], v[186:189], v[90:93]
	v_mfma_f32_16x16x32_bf16 v[78:81], v[130:133], v[194:197], v[78:81]
	v_mfma_f32_16x16x32_bf16 v[74:77], v[138:141], v[194:197], v[74:77]
	v_mfma_f32_16x16x32_bf16 v[126:129], v[134:137], v[150:153], v[126:129]
	v_mfma_f32_16x16x32_bf16 v[122:125], v[142:145], v[150:153], v[122:125]
	v_mfma_f32_16x16x32_bf16 v[110:113], v[134:137], v[158:161], v[110:113]
	v_mfma_f32_16x16x32_bf16 v[106:109], v[142:145], v[158:161], v[106:109]
	v_mfma_f32_16x16x32_bf16 v[94:97], v[134:137], v[190:193], v[94:97]
	v_mfma_f32_16x16x32_bf16 v[90:93], v[142:145], v[190:193], v[90:93]
	v_mfma_f32_16x16x32_bf16 v[78:81], v[134:137], v[214:217], v[78:81]
	v_mfma_f32_16x16x32_bf16 v[74:77], v[142:145], v[214:217], v[74:77]
	v_mfma_f32_16x16x32_bf16 v[118:121], v[232:235], v[146:149], v[118:121]
	v_mfma_f32_16x16x32_bf16 v[114:117], v[240:243], v[146:149], v[114:117]
	v_mfma_f32_16x16x32_bf16 v[102:105], v[232:235], v[154:157], v[102:105]
	v_mfma_f32_16x16x32_bf16 v[98:101], v[240:243], v[154:157], v[98:101]
	v_mfma_f32_16x16x32_bf16 v[86:89], v[232:235], v[186:189], v[86:89]
	v_mfma_f32_16x16x32_bf16 v[82:85], v[240:243], v[186:189], v[82:85]
	v_mfma_f32_16x16x32_bf16 v[70:73], v[232:235], v[194:197], v[70:73]
	v_mfma_f32_16x16x32_bf16 v[66:69], v[240:243], v[194:197], v[66:69]
	v_mfma_f32_16x16x32_bf16 v[118:121], v[236:239], v[150:153], v[118:121]
	v_mfma_f32_16x16x32_bf16 v[114:117], v[244:247], v[150:153], v[114:117]
	v_mfma_f32_16x16x32_bf16 v[102:105], v[236:239], v[158:161], v[102:105]
	v_mfma_f32_16x16x32_bf16 v[98:101], v[244:247], v[158:161], v[98:101]
	v_mfma_f32_16x16x32_bf16 v[86:89], v[236:239], v[190:193], v[86:89]
	v_mfma_f32_16x16x32_bf16 v[82:85], v[244:247], v[190:193], v[82:85]
	v_mfma_f32_16x16x32_bf16 v[70:73], v[236:239], v[214:217], v[70:73]
	v_mfma_f32_16x16x32_bf16 v[66:69], v[244:247], v[214:217], v[66:69]
	s_setprio 0
	s_barrier
	ds_read_b128 v[146:149], v212 offset:49152
	ds_read_b128 v[150:153], v212 offset:50176
	ds_read_b128 v[154:157], v212 offset:51200
	ds_read_b128 v[158:161], v212 offset:52224
	ds_read_b128 v[186:189], v212 offset:53248
	ds_read_b128 v[190:193], v212 offset:54272
	ds_read_b128 v[194:197], v212 offset:55296
	ds_read_b128 v[214:217], v212 offset:56320
	v_lshl_add_u64 v[198:199], v[198:199], 0, s[16:17]
	s_mov_b32 m0, s21
	v_lshl_add_u64 v[218:219], v[218:219], 0, s[16:17]
	global_load_lds_dwordx4 v[198:199], off
	s_add_i32 m0, s21, 0x2000
	s_nop 0
	global_load_lds_dwordx4 v[218:219], off
	s_mov_b32 m0, s97
	v_lshl_add_u64 v[248:249], v[248:249], 0, s[16:17]
	v_lshl_add_u64 v[250:251], v[250:251], 0, s[16:17]
	global_load_lds_dwordx4 v[248:249], off
	s_mov_b32 m0, s90
	s_nop 0
	global_load_lds_dwordx4 v[250:251], off
	s_add_i32 s20, s20, s30
	v_lshl_add_u64 v[226:227], v[226:227], 0, s[16:17]
	s_mov_b32 m0, s20
	v_lshl_add_u64 v[228:229], v[228:229], 0, s[16:17]
	global_load_lds_dwordx4 v[226:227], off
	s_add_i32 m0, s20, 0x2000
	s_nop 0
	global_load_lds_dwordx4 v[228:229], off
	s_waitcnt vmcnt(8) lgkmcnt(0)
	s_barrier
	s_setprio 1
	v_mfma_f32_16x16x32_bf16 v[62:65], v[130:133], v[146:149], v[62:65]
	v_mfma_f32_16x16x32_bf16 v[58:61], v[138:141], v[146:149], v[58:61]
	v_mfma_f32_16x16x32_bf16 v[46:49], v[130:133], v[154:157], v[46:49]
	v_mfma_f32_16x16x32_bf16 v[42:45], v[138:141], v[154:157], v[42:45]
	v_mfma_f32_16x16x32_bf16 v[30:33], v[130:133], v[186:189], v[30:33]
	v_mfma_f32_16x16x32_bf16 v[26:29], v[138:141], v[186:189], v[26:29]
	v_mfma_f32_16x16x32_bf16 v[14:17], v[130:133], v[194:197], v[14:17]
	v_mfma_f32_16x16x32_bf16 v[10:13], v[138:141], v[194:197], v[10:13]
	v_mfma_f32_16x16x32_bf16 v[62:65], v[134:137], v[150:153], v[62:65]
	v_mfma_f32_16x16x32_bf16 v[58:61], v[142:145], v[150:153], v[58:61]
	v_mfma_f32_16x16x32_bf16 v[46:49], v[134:137], v[158:161], v[46:49]
	v_mfma_f32_16x16x32_bf16 v[42:45], v[142:145], v[158:161], v[42:45]
	v_mfma_f32_16x16x32_bf16 v[30:33], v[134:137], v[190:193], v[30:33]
	v_mfma_f32_16x16x32_bf16 v[26:29], v[142:145], v[190:193], v[26:29]
	v_mfma_f32_16x16x32_bf16 v[14:17], v[134:137], v[214:217], v[14:17]
	v_mfma_f32_16x16x32_bf16 v[10:13], v[142:145], v[214:217], v[10:13]
	v_mfma_f32_16x16x32_bf16 v[54:57], v[232:235], v[146:149], v[54:57]
	v_mfma_f32_16x16x32_bf16 v[50:53], v[240:243], v[146:149], v[50:53]
	v_mfma_f32_16x16x32_bf16 v[38:41], v[232:235], v[154:157], v[38:41]
	v_mfma_f32_16x16x32_bf16 v[34:37], v[240:243], v[154:157], v[34:37]
	v_mfma_f32_16x16x32_bf16 v[22:25], v[232:235], v[186:189], v[22:25]
	v_mfma_f32_16x16x32_bf16 v[18:21], v[240:243], v[186:189], v[18:21]
	v_mfma_f32_16x16x32_bf16 v[6:9], v[232:235], v[194:197], v[6:9]
	v_mfma_f32_16x16x32_bf16 v[2:5], v[240:243], v[194:197], v[2:5]
	v_mfma_f32_16x16x32_bf16 v[54:57], v[236:239], v[150:153], v[54:57]
	v_mfma_f32_16x16x32_bf16 v[50:53], v[244:247], v[150:153], v[50:53]
	v_mfma_f32_16x16x32_bf16 v[38:41], v[236:239], v[158:161], v[38:41]
	v_mfma_f32_16x16x32_bf16 v[34:37], v[244:247], v[158:161], v[34:37]
	v_mfma_f32_16x16x32_bf16 v[22:25], v[236:239], v[190:193], v[22:25]
	v_mfma_f32_16x16x32_bf16 v[18:21], v[244:247], v[190:193], v[18:21]
	v_mfma_f32_16x16x32_bf16 v[6:9], v[236:239], v[214:217], v[6:9]
	v_mfma_f32_16x16x32_bf16 v[2:5], v[244:247], v[214:217], v[2:5]
	s_setprio 0
	s_add_u32 s38, s38, 0x100
	s_addc_u32 s39, s39, 0
	s_add_u32 s18, s18, 0x100
	s_addc_u32 s19, s19, 0
	s_cmp_ge_u32 s42, s91
	s_mov_b32 s20, s42
	s_barrier
	s_cbranch_scc0 .LBB0_919
	s_branch .Lkloop_done
.Lkloop_narrow:
	s_add_i32 s42, s20, 2
	s_add_u32 s24, s18, 0x80
	s_addc_u32 s21, s19, 0
	s_add_i32 s43, 0, 0x10000
	v_add_u32_e32 v0, s43, v211
	s_waitcnt lgkmcnt(0)
	ds_read_b128 v[130:133], v0
	ds_read_b128 v[134:137], v0 offset:1024
	ds_read_b128 v[138:141], v0 offset:2048
	ds_read_b128 v[142:145], v0 offset:3072
	s_cmp_eq_u32 s66, s20
	s_cselect_b32 s20, s74, s24
	s_cselect_b32 s21, s75, s21
	s_cselect_b32 s25, s77, s39
	s_cselect_b32 s24, s76, s38
	s_add_i32 s44, 0, 0x14000
	v_add_u32_e32 v0, s44, v211
	v_lshl_add_u64 v[198:199], s[18:19], 0, v[184:185]
	s_add_i32 m0, s31, 0xc000
	global_load_lds_dwordx4 v[198:199], off
	v_lshl_add_u64 v[198:199], s[18:19], 0, v[182:183]
	s_add_i32 m0, s31, 0xe000
	s_nop 0
	global_load_lds_dwordx4 v[198:199], off
	ds_read_b128 v[146:149], v212
	ds_read_b128 v[150:153], v212 offset:1024
	ds_read_b128 v[154:157], v212 offset:2048
	ds_read_b128 v[158:161], v212 offset:3072
	ds_read_b128 v[186:189], v212 offset:4096
	ds_read_b128 v[190:193], v212 offset:5120
	s_waitcnt lgkmcnt(12)
	ds_read_b128 v[194:197], v212 offset:6144
	ds_read_b128 v[214:217], v212 offset:7168
	s_waitcnt vmcnt(8) lgkmcnt(0)
	s_barrier
	s_setprio 1
	v_mfma_f32_16x16x32_bf16 v[126:129], v[130:133], v[146:149], v[126:129]
	v_mfma_f32_16x16x32_bf16 v[122:125], v[138:141], v[146:149], v[122:125]
	v_mfma_f32_16x16x32_bf16 v[110:113], v[130:133], v[154:157], v[110:113]
	v_mfma_f32_16x16x32_bf16 v[106:109], v[138:141], v[154:157], v[106:109]
	v_mfma_f32_16x16x32_bf16 v[94:97], v[130:133], v[186:189], v[94:97]
	v_mfma_f32_16x16x32_bf16 v[90:93], v[138:141], v[186:189], v[90:93]
	v_mfma_f32_16x16x32_bf16 v[78:81], v[130:133], v[194:197], v[78:81]
	v_mfma_f32_16x16x32_bf16 v[74:77], v[138:141], v[194:197], v[74:77]
	v_mfma_f32_16x16x32_bf16 v[126:129], v[134:137], v[150:153], v[126:129]
	v_mfma_f32_16x16x32_bf16 v[122:125], v[142:145], v[150:153], v[122:125]
	v_mfma_f32_16x16x32_bf16 v[110:113], v[134:137], v[158:161], v[110:113]
	v_mfma_f32_16x16x32_bf16 v[106:109], v[142:145], v[158:161], v[106:109]
	v_mfma_f32_16x16x32_bf16 v[94:97], v[134:137], v[190:193], v[94:97]
	v_mfma_f32_16x16x32_bf16 v[90:93], v[142:145], v[190:193], v[90:93]
	v_mfma_f32_16x16x32_bf16 v[78:81], v[134:137], v[214:217], v[78:81]
	v_mfma_f32_16x16x32_bf16 v[74:77], v[142:145], v[214:217], v[74:77]
	s_setprio 0
	s_barrier
	ds_read_b128 v[146:149], v212 offset:16384
	ds_read_b128 v[150:153], v212 offset:17408
	ds_read_b128 v[154:157], v212 offset:18432
	ds_read_b128 v[158:161], v212 offset:19456
	ds_read_b128 v[186:189], v212 offset:20480
	ds_read_b128 v[190:193], v212 offset:21504
	ds_read_b128 v[194:197], v212 offset:22528
	ds_read_b128 v[214:217], v212 offset:23552
	s_add_i32 s43, s43, s30
	v_lshl_add_u64 v[198:199], s[24:25], 0, v[170:171]
	s_mov_b32 m0, s43
	v_lshl_add_u64 v[218:219], s[24:25], 0, v[174:175]
	global_load_lds_dwordx4 v[198:199], off
	s_add_i32 m0, s43, 0x2000
	s_nop 0
	global_load_lds_dwordx4 v[218:219], off
	s_mov_b32 m0, s31
	v_lshl_add_u64 v[248:249], s[20:21], 0, v[168:169]
	v_lshl_add_u64 v[250:251], s[20:21], 0, v[172:173]
	global_load_lds_dwordx4 v[248:249], off
	s_mov_b32 m0, s95
	s_nop 0
	global_load_lds_dwordx4 v[250:251], off
	s_add_u32 s24, s24, s60
	s_addc_u32 s25, s25, 0
	s_add_i32 s43, s44, s30
	v_lshl_add_u64 v[226:227], s[24:25], 0, v[170:171]
	s_mov_b32 m0, s43
	v_lshl_add_u64 v[228:229], s[24:25], 0, v[174:175]
	global_load_lds_dwordx4 v[226:227], off
	s_add_i32 m0, s43, 0x2000
	s_nop 0
	global_load_lds_dwordx4 v[228:229], off
	s_waitcnt vmcnt(8) lgkmcnt(0)
	s_barrier
	s_setprio 1
	v_mfma_f32_16x16x32_bf16 v[62:65], v[130:133], v[146:149], v[62:65]
	v_mfma_f32_16x16x32_bf16 v[58:61], v[138:141], v[146:149], v[58:61]
	v_mfma_f32_16x16x32_bf16 v[46:49], v[130:133], v[154:157], v[46:49]
	v_mfma_f32_16x16x32_bf16 v[42:45], v[138:141], v[154:157], v[42:45]
	v_mfma_f32_16x16x32_bf16 v[30:33], v[130:133], v[186:189], v[30:33]
	v_mfma_f32_16x16x32_bf16 v[26:29], v[138:141], v[186:189], v[26:29]
	v_mfma_f32_16x16x32_bf16 v[14:17], v[130:133], v[194:197], v[14:17]
	v_mfma_f32_16x16x32_bf16 v[10:13], v[138:141], v[194:197], v[10:13]
	v_mfma_f32_16x16x32_bf16 v[62:65], v[134:137], v[150:153], v[62:65]
	v_mfma_f32_16x16x32_bf16 v[58:61], v[142:145], v[150:153], v[58:61]
	v_mfma_f32_16x16x32_bf16 v[46:49], v[134:137], v[158:161], v[46:49]
	v_mfma_f32_16x16x32_bf16 v[42:45], v[142:145], v[158:161], v[42:45]
	v_mfma_f32_16x16x32_bf16 v[30:33], v[134:137], v[190:193], v[30:33]
	v_mfma_f32_16x16x32_bf16 v[26:29], v[142:145], v[190:193], v[26:29]
	v_mfma_f32_16x16x32_bf16 v[14:17], v[134:137], v[214:217], v[14:17]
	v_mfma_f32_16x16x32_bf16 v[10:13], v[142:145], v[214:217], v[10:13]
	s_setprio 0
	s_barrier
	s_add_u32 s20, s20, s60
	s_addc_u32 s21, s21, 0
	s_mov_b32 m0, s8
	v_lshl_add_u64 v[232:233], s[20:21], 0, v[168:169]
	s_add_i32 s24, 0, 0x18000
	v_add_u32_e32 v0, s24, v211
	global_load_lds_dwordx4 v[232:233], off
	v_lshl_add_u64 v[232:233], s[20:21], 0, v[172:173]
	s_mov_b32 m0, s9
	s_nop 0
	global_load_lds_dwordx4 v[232:233], off
	ds_read_b128 v[130:133], v0
	ds_read_b128 v[134:137], v0 offset:1024
	ds_read_b128 v[138:141], v0 offset:2048
	ds_read_b128 v[142:145], v0 offset:3072
	s_add_i32 s20, 0, 0x1c000
	s_add_i32 s21, s24, s30
	v_add_u32_e32 v0, s20, v211
	ds_read_b128 v[146:149], v212 offset:32768
	ds_read_b128 v[150:153], v212 offset:33792
	ds_read_b128 v[154:157], v212 offset:34816
	ds_read_b128 v[158:161], v212 offset:35840
	ds_read_b128 v[186:189], v212 offset:36864
	ds_read_b128 v[190:193], v212 offset:37888
	s_waitcnt lgkmcnt(12)
	ds_read_b128 v[194:197], v212 offset:38912
	ds_read_b128 v[214:217], v212 offset:39936
	s_waitcnt vmcnt(8) lgkmcnt(0)
	s_barrier
	s_setprio 1
	v_mfma_f32_16x16x32_bf16 v[126:129], v[130:133], v[146:149], v[126:129]
	v_mfma_f32_16x16x32_bf16 v[122:125], v[138:141], v[146:149], v[122:125]
	v_mfma_f32_16x16x32_bf16 v[110:113], v[130:133], v[154:157], v[110:113]
	v_mfma_f32_16x16x32_bf16 v[106:109], v[138:141], v[154:157], v[106:109]
	v_mfma_f32_16x16x32_bf16 v[94:97], v[130:133], v[186:189], v[94:97]
	v_mfma_f32_16x16x32_bf16 v[90:93], v[138:141], v[186:189], v[90:93]
	v_mfma_f32_16x16x32_bf16 v[78:81], v[130:133], v[194:197], v[78:81]
	v_mfma_f32_16x16x32_bf16 v[74:77], v[138:141], v[194:197], v[74:77]
	v_mfma_f32_16x16x32_bf16 v[126:129], v[134:137], v[150:153], v[126:129]
	v_mfma_f32_16x16x32_bf16 v[122:125], v[142:145], v[150:153], v[122:125]
	v_mfma_f32_16x16x32_bf16 v[110:113], v[134:137], v[158:161], v[110:113]
	v_mfma_f32_16x16x32_bf16 v[106:109], v[142:145], v[158:161], v[106:109]
	v_mfma_f32_16x16x32_bf16 v[94:97], v[134:137], v[190:193], v[94:97]
	v_mfma_f32_16x16x32_bf16 v[90:93], v[142:145], v[190:193], v[90:93]
	v_mfma_f32_16x16x32_bf16 v[78:81], v[134:137], v[214:217], v[78:81]
	v_mfma_f32_16x16x32_bf16 v[74:77], v[142:145], v[214:217], v[74:77]
	s_setprio 0
	s_barrier
	ds_read_b128 v[146:149], v212 offset:49152
	ds_read_b128 v[150:153], v212 offset:50176
	ds_read_b128 v[154:157], v212 offset:51200
	ds_read_b128 v[158:161], v212 offset:52224
	ds_read_b128 v[186:189], v212 offset:53248
	ds_read_b128 v[190:193], v212 offset:54272
	ds_read_b128 v[194:197], v212 offset:55296
	ds_read_b128 v[214:217], v212 offset:56320
	v_lshl_add_u64 v[198:199], v[198:199], 0, s[16:17]
	s_mov_b32 m0, s21
	v_lshl_add_u64 v[218:219], v[218:219], 0, s[16:17]
	global_load_lds_dwordx4 v[198:199], off
	s_add_i32 m0, s21, 0x2000
	s_nop 0
	global_load_lds_dwordx4 v[218:219], off
	s_mov_b32 m0, s97
	v_lshl_add_u64 v[248:249], v[248:249], 0, s[16:17]
	v_lshl_add_u64 v[250:251], v[250:251], 0, s[16:17]
	global_load_lds_dwordx4 v[248:249], off
	s_mov_b32 m0, s90
	s_nop 0
	global_load_lds_dwordx4 v[250:251], off
	s_add_i32 s20, s20, s30
	v_lshl_add_u64 v[226:227], v[226:227], 0, s[16:17]
	s_mov_b32 m0, s20
	v_lshl_add_u64 v[228:229], v[228:229], 0, s[16:17]
	global_load_lds_dwordx4 v[226:227], off
	s_add_i32 m0, s20, 0x2000
	s_nop 0
	global_load_lds_dwordx4 v[228:229], off
	s_waitcnt vmcnt(8) lgkmcnt(0)
	s_barrier
	s_setprio 1
	v_mfma_f32_16x16x32_bf16 v[62:65], v[130:133], v[146:149], v[62:65]
	v_mfma_f32_16x16x32_bf16 v[58:61], v[138:141], v[146:149], v[58:61]
	v_mfma_f32_16x16x32_bf16 v[46:49], v[130:133], v[154:157], v[46:49]
	v_mfma_f32_16x16x32_bf16 v[42:45], v[138:141], v[154:157], v[42:45]
	v_mfma_f32_16x16x32_bf16 v[30:33], v[130:133], v[186:189], v[30:33]
	v_mfma_f32_16x16x32_bf16 v[26:29], v[138:141], v[186:189], v[26:29]
	v_mfma_f32_16x16x32_bf16 v[14:17], v[130:133], v[194:197], v[14:17]
	v_mfma_f32_16x16x32_bf16 v[10:13], v[138:141], v[194:197], v[10:13]
	v_mfma_f32_16x16x32_bf16 v[62:65], v[134:137], v[150:153], v[62:65]
	v_mfma_f32_16x16x32_bf16 v[58:61], v[142:145], v[150:153], v[58:61]
	v_mfma_f32_16x16x32_bf16 v[46:49], v[134:137], v[158:161], v[46:49]
	v_mfma_f32_16x16x32_bf16 v[42:45], v[142:145], v[158:161], v[42:45]
	v_mfma_f32_16x16x32_bf16 v[30:33], v[134:137], v[190:193], v[30:33]
	v_mfma_f32_16x16x32_bf16 v[26:29], v[142:145], v[190:193], v[26:29]
	v_mfma_f32_16x16x32_bf16 v[14:17], v[134:137], v[214:217], v[14:17]
	v_mfma_f32_16x16x32_bf16 v[10:13], v[142:145], v[214:217], v[10:13]
	s_setprio 0
	s_add_u32 s38, s38, 0x100
	s_addc_u32 s39, s39, 0
	s_add_u32 s18, s18, 0x100
	s_addc_u32 s19, s19, 0
	s_cmp_ge_u32 s42, s91
	s_mov_b32 s20, s42
	s_barrier
	s_cbranch_scc0 .Lkloop_narrow
